# stack25: QKV epilogue last column group skips its counted rope waits when the group has no rope (on top of stack24)
# baseline (speedup 1.0000x reference)
; __device__ __forceinline__ unsigned cvt_pk_bf16(float lo, float hi) { unsigned r; asm volatile("v_cvt_pk_bf16_f32 %0, %1, %2" : "=v"(r) : "v"(lo), "v"(hi)); return r; }
;     __device__ __forceinline__ void operator()(const f32x4 (&acc)[2][2][4][2], const Unit& u, int wr, int wc, int fr_in, int fq_in) const {
;     ...
;                     if (isrope) {
; #pragma unroll
;                         for (int m = 0; m < 4; ++m) { const int row = row0 + ai * HALF + m * 16; cs[m] = *(const f32x4*)(CS + (size_t)row * 32 + 4 * fq); sn[m] = *(const f32x4*)(CS + (size_t)row * 32 + 16 + 4 * fq); }
;                     }
;                     __builtin_amdgcn_sched_barrier(0);
; #pragma unroll
;                     for (int m = 0; m < 4; ++m) { const int row = row0 + ai * HALF + m * 16;
;                         f32x4 v0 = acc[ai][bj][m][0], v1 = acc[ai][bj][m][1];
;                         if (isrope) { const f32x4 o0 = v0 * cs[m] - v1 * sn[m], o1 = v1 * cs[m] + v0 * sn[m]; v0 = o0; v1 = o1; }
;                         v0 = v0 * QSCALE; v1 = v1 * QSCALE;
;                         bf16_t* p = Q + (size_t)row * QW + X + 4 * fq;
;                         u32x2 a; a.x = cvt_pk_bf16(v0[0], v0[1]); a.y = cvt_pk_bf16(v0[2], v0[3]); *(u32x2*)p = a;
;                         u32x2 b; b.x = cvt_pk_bf16(v1[0], v1[1]); b.y = cvt_pk_bf16(v1[2], v1[3]); *(u32x2*)(p + 16) = b; }
.LBB0_295:
	s_and_b64 vcc, exec, s[40:41]
	s_cbranch_vccz .Lrope_skip0
	s_waitcnt vmcnt(6)
.Lrope_skip0:
	v_pk_mul_f32 v[40:41], v[28:29], v[96:97]
	v_readlane_b32 s4, v240, 27
	v_pk_mul_f32 v[42:43], v[26:27], v[94:95]
	v_pk_fma_f32 v[40:41], v[32:33], v[100:101], v[40:41] neg_lo:[0,0,1] neg_hi:[0,0,1]
	v_pk_mul_f32 v[44:45], v[28:29], v[100:101]
	v_readlane_b32 s5, v240, 28
	v_pk_fma_f32 v[42:43], v[30:31], v[98:99], v[42:43] neg_lo:[0,0,1] neg_hi:[0,0,1]
	v_pk_mul_f32 v[46:47], v[26:27], v[98:99]
	v_pk_fma_f32 v[44:45], v[32:33], v[96:97], v[44:45]
	v_cndmask_b32_e64 v33, v33, v41, s[40:41]
	v_cndmask_b32_e64 v32, v32, v40, s[40:41]
	v_mov_b64_e32 v[40:41], s[4:5]
	v_pk_fma_f32 v[46:47], v[30:31], v[94:95], v[46:47]
	v_cndmask_b32_e64 v31, v31, v43, s[40:41]
	v_cndmask_b32_e64 v30, v30, v42, s[40:41]
	v_mad_u64_u32 v[42:43], s[4:5], v0, s14, v[40:41]
	v_cndmask_b32_e64 v27, v27, v47, s[40:41]
	v_cndmask_b32_e64 v26, v26, v46, s[40:41]
	v_lshl_add_u64 v[42:43], v[42:43], 0, s[50:51]
	v_cndmask_b32_e64 v29, v29, v45, s[40:41]
	v_cndmask_b32_e64 v28, v28, v44, s[40:41]
	v_pk_mul_f32 v[30:31], v[30:31], s[2:3] op_sel_hi:[1,0]
	v_pk_mul_f32 v[26:27], v[26:27], s[2:3] op_sel_hi:[1,0]
	v_lshl_add_u64 v[42:43], v[42:43], 0, v[58:59]
	v_pk_mul_f32 v[32:33], v[32:33], s[2:3] op_sel_hi:[1,0]
	v_pk_mul_f32 v[28:29], v[28:29], s[2:3] op_sel_hi:[1,0]
	v_cvt_pk_bf16_f32 v30, v30, v31
	v_cvt_pk_bf16_f32 v31, v32, v33
	global_store_dwordx2 v[42:43], v[30:31], off offset:256
	v_cvt_pk_bf16_f32 v26, v26, v27
	v_cvt_pk_bf16_f32 v27, v28, v29
	global_store_dwordx2 v[42:43], v[26:27], off offset:288
	s_and_b64 vcc, exec, s[40:41]
	s_cbranch_vccz .Lrope_skip1
	s_waitcnt vmcnt(6)
.Lrope_skip1:
	v_pk_mul_f32 v[26:27], v[20:21], v[84:85]
	v_pk_mul_f32 v[30:31], v[20:21], v[88:89]
	v_pk_fma_f32 v[26:27], v[24:25], v[88:89], v[26:27] neg_lo:[0,0,1] neg_hi:[0,0,1]
	v_pk_mul_f32 v[28:29], v[18:19], v[82:83]
	v_pk_fma_f32 v[30:31], v[24:25], v[84:85], v[30:31]
	v_cndmask_b32_e64 v25, v25, v27, s[40:41]
	v_cndmask_b32_e64 v24, v24, v26, s[40:41]
	v_mad_u64_u32 v[26:27], s[4:5], v38, s14, v[40:41]
	v_pk_fma_f32 v[28:29], v[22:23], v[86:87], v[28:29] neg_lo:[0,0,1] neg_hi:[0,0,1]
	v_pk_mul_f32 v[32:33], v[18:19], v[86:87]
	v_mov_b32_e32 v0, v27
	v_pk_fma_f32 v[32:33], v[22:23], v[82:83], v[32:33]
	v_cndmask_b32_e64 v23, v23, v29, s[40:41]
	v_cndmask_b32_e64 v22, v22, v28, s[40:41]
	v_mad_u64_u32 v[28:29], s[4:5], v39, s14, v[0:1]
	v_mov_b32_e32 v27, v28
	v_cndmask_b32_e64 v19, v19, v33, s[40:41]
	v_cndmask_b32_e64 v18, v18, v32, s[40:41]
	v_lshl_add_u64 v[26:27], v[26:27], 0, s[50:51]
	v_cndmask_b32_e64 v21, v21, v31, s[40:41]
	v_cndmask_b32_e64 v20, v20, v30, s[40:41]
	v_pk_mul_f32 v[22:23], v[22:23], s[2:3] op_sel_hi:[1,0]
	v_pk_mul_f32 v[18:19], v[18:19], s[2:3] op_sel_hi:[1,0]
	v_lshl_add_u64 v[26:27], v[26:27], 0, v[58:59]
	v_pk_mul_f32 v[24:25], v[24:25], s[2:3] op_sel_hi:[1,0]
	v_pk_mul_f32 v[20:21], v[20:21], s[2:3] op_sel_hi:[1,0]
	v_cvt_pk_bf16_f32 v22, v22, v23
	v_cvt_pk_bf16_f32 v23, v24, v25
	global_store_dwordx2 v[26:27], v[22:23], off offset:256
	v_cvt_pk_bf16_f32 v18, v18, v19
	v_cvt_pk_bf16_f32 v19, v20, v21
	global_store_dwordx2 v[26:27], v[18:19], off offset:288
	s_and_b64 vcc, exec, s[40:41]
	s_cbranch_vccz .Lrope_skip2
	s_waitcnt vmcnt(6)
.Lrope_skip2:
	v_pk_mul_f32 v[18:19], v[12:13], v[68:69]
	v_pk_mul_f32 v[22:23], v[12:13], v[72:73]
	v_pk_fma_f32 v[18:19], v[16:17], v[72:73], v[18:19] neg_lo:[0,0,1] neg_hi:[0,0,1]
	v_pk_mul_f32 v[20:21], v[10:11], v[66:67]
	v_pk_fma_f32 v[22:23], v[16:17], v[68:69], v[22:23]
	v_cndmask_b32_e64 v17, v17, v19, s[40:41]
	v_cndmask_b32_e64 v16, v16, v18, s[40:41]
	v_mad_u64_u32 v[18:19], s[4:5], v36, s14, v[40:41]
	v_pk_fma_f32 v[20:21], v[14:15], v[70:71], v[20:21] neg_lo:[0,0,1] neg_hi:[0,0,1]
	v_pk_mul_f32 v[24:25], v[10:11], v[70:71]
	v_mov_b32_e32 v0, v19
	v_pk_fma_f32 v[24:25], v[14:15], v[66:67], v[24:25]
	v_cndmask_b32_e64 v15, v15, v21, s[40:41]
	v_cndmask_b32_e64 v14, v14, v20, s[40:41]
	v_mad_u64_u32 v[20:21], s[4:5], v37, s14, v[0:1]
	v_mov_b32_e32 v19, v20
	v_cndmask_b32_e64 v11, v11, v25, s[40:41]
	v_cndmask_b32_e64 v10, v10, v24, s[40:41]
	v_lshl_add_u64 v[18:19], v[18:19], 0, s[50:51]
	v_cndmask_b32_e64 v13, v13, v23, s[40:41]
	v_cndmask_b32_e64 v12, v12, v22, s[40:41]
	v_pk_mul_f32 v[14:15], v[14:15], s[2:3] op_sel_hi:[1,0]
	v_pk_mul_f32 v[10:11], v[10:11], s[2:3] op_sel_hi:[1,0]
	v_lshl_add_u64 v[18:19], v[18:19], 0, v[58:59]
	v_pk_mul_f32 v[16:17], v[16:17], s[2:3] op_sel_hi:[1,0]
	v_pk_mul_f32 v[12:13], v[12:13], s[2:3] op_sel_hi:[1,0]
	v_cvt_pk_bf16_f32 v14, v14, v15
	v_cvt_pk_bf16_f32 v15, v16, v17
	global_store_dwordx2 v[18:19], v[14:15], off offset:256
	v_cvt_pk_bf16_f32 v10, v10, v11
	v_cvt_pk_bf16_f32 v11, v12, v13
	global_store_dwordx2 v[18:19], v[10:11], off offset:288
	s_and_b64 vcc, exec, s[40:41]
	s_cbranch_vccz .Lrope_skip3
	s_waitcnt vmcnt(6)
.Lrope_skip3:
	v_pk_mul_f32 v[10:11], v[4:5], v[104:105]
	v_pk_mul_f32 v[14:15], v[4:5], v[92:93]
	v_pk_fma_f32 v[10:11], v[8:9], v[92:93], v[10:11] neg_lo:[0,0,1] neg_hi:[0,0,1]
	v_pk_mul_f32 v[12:13], v[2:3], v[102:103]
	v_pk_fma_f32 v[14:15], v[8:9], v[104:105], v[14:15]
	v_cndmask_b32_e64 v9, v9, v11, s[40:41]
	v_cndmask_b32_e64 v8, v8, v10, s[40:41]
	v_mad_u64_u32 v[10:11], s[4:5], v34, s14, v[40:41]
	v_pk_fma_f32 v[12:13], v[6:7], v[90:91], v[12:13] neg_lo:[0,0,1] neg_hi:[0,0,1]
	v_pk_mul_f32 v[16:17], v[2:3], v[90:91]
	v_mov_b32_e32 v0, v11
	v_pk_fma_f32 v[16:17], v[6:7], v[102:103], v[16:17]
	v_cndmask_b32_e64 v7, v7, v13, s[40:41]
	v_cndmask_b32_e64 v6, v6, v12, s[40:41]
	v_mad_u64_u32 v[12:13], s[4:5], v35, s14, v[0:1]
	v_mov_b32_e32 v11, v12
	v_cndmask_b32_e64 v3, v3, v17, s[40:41]
	v_cndmask_b32_e64 v2, v2, v16, s[40:41]
	v_lshl_add_u64 v[10:11], v[10:11], 0, s[50:51]
	v_cndmask_b32_e64 v5, v5, v15, s[40:41]
	v_cndmask_b32_e64 v4, v4, v14, s[40:41]
	v_pk_mul_f32 v[6:7], v[6:7], s[2:3] op_sel_hi:[1,0]
	v_pk_mul_f32 v[2:3], v[2:3], s[2:3] op_sel_hi:[1,0]
	v_lshl_add_u64 v[10:11], v[10:11], 0, v[58:59]
	v_pk_mul_f32 v[8:9], v[8:9], s[2:3] op_sel_hi:[1,0]
	v_pk_mul_f32 v[4:5], v[4:5], s[2:3] op_sel_hi:[1,0]
	v_cvt_pk_bf16_f32 v6, v6, v7
	v_cvt_pk_bf16_f32 v7, v8, v9
	global_store_dwordx2 v[10:11], v[6:7], off offset:256
	v_cvt_pk_bf16_f32 v2, v2, v3
	v_cvt_pk_bf16_f32 v3, v4, v5
	global_store_dwordx2 v[10:11], v[2:3], off offset:288
	s_andn2_b64 vcc, exec, s[44:45]
	s_mov_b64 s[40:41], -1
	s_cbranch_vccnz .LBB0_260
	s_branch .LBB0_303
